# FoX forget-gate cumsum: the 8 per-thread loads issued together and kept in registers for the second pass (was 15 serialized round trips)
# speedup vs baseline: 1.0101x; 1.0032x over previous
; #define otid() otid_(wid_k)
; __global__ void __launch_bounds__(NTHR, 2) fwd_kernel(Params p) {
;     ...
;       if (c >= 176) {
;         const int tid = otid();
;         const int bh = c - 176, b = bh >> 2, h = bh & 3;
;         const float* flog = WSP(float, OFF_FLOG); float* cum = WSP(float, OFF_CUM);
;         float run = 0.f;
; #pragma unroll
;         for (int e = 0; e < 8; ++e) run += flog[((size_t)b * SEQ + tid * 8 + e) * 4 + h];
;         __syncthreads();
;         ldsf[tid] = run;
;         __syncthreads();
;         float base = 0.f;
;         for (int j = 0; j < tid; ++j) base += ldsf[j];
.LBB0_1239:
	s_andn2_b64 vcc, exec, s[4:5]
	s_cbranch_vccnz .LBB0_1251
	v_mbcnt_lo_u32_b32 v7, -1, 0
	v_mbcnt_hi_u32_b32 v7, -1, v7
	s_add_i32 s10, s8, 0xffffff10
	v_or_b32_e32 v6, s97, v7
	s_lshr_b32 s4, s10, 2
	s_mov_b32 s5, s73
	v_lshlrev_b32_e32 v4, 3, v6
	s_and_b32 s6, s8, 3
	s_lshl_b64 s[4:5], s[4:5], 12
	v_ashrrev_i32_e32 v5, 31, v4
	v_lshl_add_u64 v[2:3], s[4:5], 0, v[4:5]
	s_lshl_b32 s4, s6, 2
	s_add_u32 s4, s2, s4
	s_addc_u32 s5, s3, 0
	v_lshl_add_u64 v[8:9], v[2:3], 4, s[4:5]
	s_mov_b64 s[4:5], 0x770000
	v_lshl_add_u64 v[2:3], v[8:9], 0, s[4:5]
	s_mov_b32 s4, 0x770000
	v_add_co_u32_e32 v8, vcc, s4, v8
	v_mov_b32_e32 v0, 0
	s_nop 0
	v_addc_co_u32_e32 v9, vcc, 0, v9, vcc
	global_load_dword v16, v[8:9], off
	v_cmp_lt_i32_e32 vcc, 0, v6
	global_load_dword v17, v[2:3], off offset:16
	global_load_dword v18, v[2:3], off offset:32
	global_load_dword v19, v[2:3], off offset:48
	global_load_dword v20, v[2:3], off offset:64
	global_load_dword v21, v[2:3], off offset:80
	global_load_dword v22, v[2:3], off offset:96
	global_load_dword v23, v[2:3], off offset:112
	s_waitcnt vmcnt(7)
	v_add_f32_e32 v5, 0, v16
	s_waitcnt vmcnt(6)
	v_add_f32_e32 v5, v5, v17
	s_waitcnt vmcnt(5)
	v_add_f32_e32 v5, v5, v18
	s_waitcnt vmcnt(4)
	v_add_f32_e32 v5, v5, v19
	s_waitcnt vmcnt(3)
	v_add_f32_e32 v5, v5, v20
	s_waitcnt vmcnt(2)
	v_add_f32_e32 v5, v5, v21
	s_waitcnt vmcnt(1)
	v_add_f32_e32 v5, v5, v22
	s_barrier
	s_waitcnt vmcnt(0)
	v_add_f32_e32 v5, v5, v23
	v_lshl_add_u32 v8, v6, 2, 0
	ds_write_b32 v8, v5
	s_waitcnt lgkmcnt(0)
	s_barrier
	s_and_saveexec_b64 s[4:5], vcc
	s_cbranch_execz .LBB0_1250
	v_and_b32_e32 v5, 7, v7
	v_cmp_lt_u32_e32 vcc, 7, v6
	v_mov_b32_e32 v0, 0
	v_mov_b32_e32 v7, 0
	s_and_saveexec_b64 s[6:7], vcc
	s_cbranch_execz .LBB0_1245
	v_sub_u32_e32 v7, v6, v5
	s_mov_b32 s11, 0
	s_mov_b32 s12, 0
	s_mov_b64 s[8:9], 0
	v_mov_b32_e32 v0, 0

; __global__ void __launch_bounds__(NTHR, 2) fwd_kernel(Params p) {
;     ...
; #pragma unroll
;         for (int e = 0; e < 8; ++e) { base += flog[((size_t)b * SEQ + tid * 8 + e) * 4 + h]; cum[bh * SEQ + tid * 8 + e] = base * 1.44269504f; }
;         __syncthreads();
.LBB0_1250:
	s_or_b64 exec, exec, s[4:5]
	v_lshl_add_u32 v4, s10, 12, v4
	v_ashrrev_i32_e32 v5, 31, v4
	v_lshl_add_u64 v[4:5], v[4:5], 2, s[2:3]
	v_add_co_u32_e32 v6, vcc, 0x7b0000, v4
	s_mov_b64 s[4:5], 0x7b0000
	s_nop 0
	v_addc_co_u32_e32 v7, vcc, 0, v5, vcc
	v_lshl_add_u64 v[4:5], v[4:5], 0, s[4:5]
	v_add_f32_e32 v0, v0, v16
	v_mul_f32_e32 v8, 0x3fb8aa3b, v0
	global_store_dword v[6:7], v8, off
	v_add_f32_e32 v0, v0, v17
	v_mul_f32_e32 v9, 0x3fb8aa3b, v0
	global_store_dword v[4:5], v9, off offset:4
	v_add_f32_e32 v0, v0, v18
	v_mul_f32_e32 v10, 0x3fb8aa3b, v0
	global_store_dword v[4:5], v10, off offset:8
	v_add_f32_e32 v0, v0, v19
	v_mul_f32_e32 v11, 0x3fb8aa3b, v0
	global_store_dword v[4:5], v11, off offset:12
	v_add_f32_e32 v0, v0, v20
	v_mul_f32_e32 v12, 0x3fb8aa3b, v0
	global_store_dword v[4:5], v12, off offset:16
	v_add_f32_e32 v0, v0, v21
	v_mul_f32_e32 v13, 0x3fb8aa3b, v0
	global_store_dword v[4:5], v13, off offset:20
	v_add_f32_e32 v0, v0, v22
	v_mul_f32_e32 v14, 0x3fb8aa3b, v0
	global_store_dword v[4:5], v14, off offset:24
	v_add_f32_e32 v0, v0, v23
	v_mul_f32_e32 v15, 0x3fb8aa3b, v0
	global_store_dword v[4:5], v15, off offset:28
	s_barrier
